# v41 + sc1 write-through on PROJ stores of the W_in epilogue
# baseline (speedup 1.0000x reference)
.LBB0_446:
	s_lshl_b32 s0, s24, 8
	s_mul_i32 s1, s24, 0x240000
	v_mov_b32_e32 v140, v142
	v_mov_b32_e32 v141, v143
	s_mul_hi_i32 s0, s0, 0x2400
	s_add_u32 s1, s45, s1
	s_addc_u32 s0, s46, s0
	v_add_u32_e32 v147, s47, v140
	s_lshl_b32 s26, s50, 8
	s_ashr_i32 s27, s26, 31
	v_lshlrev_b32_e32 v140, 3, v141
	v_lshl_add_u32 v141, v147, 2, 0
	s_lshl_b64 s[26:27], s[26:27], 1
	v_add_u32_e32 v152, 0x20400, v141
	s_add_u32 s1, s1, s26
	ds_read_b32 v146, v152
	s_addc_u32 s0, s0, s27
	s_add_u32 s26, s1, s49
	s_addc_u32 s27, s0, 0
	v_ashrrev_i32_e32 v141, 31, v140
	v_lshl_add_u64 v[140:141], v[140:141], 1, s[26:27]
	v_mad_i64_i32 v[148:149], s[26:27], v147, s96, v[140:141]
	s_waitcnt lgkmcnt(0)
	v_pk_mul_f32 v[128:129], v[128:129], v[146:147] op_sel_hi:[1,0]
	v_pk_mul_f32 v[126:127], v[126:127], v[146:147] op_sel_hi:[1,0]
	v_pk_mul_f32 v[150:151], v[124:125], v[146:147] op_sel_hi:[1,0]
	v_pk_mul_f32 v[124:125], v[122:123], v[146:147] op_sel_hi:[1,0]
	v_cvt_pk_bf16_f32 v122, v126, v127
	v_cvt_pk_bf16_f32 v123, v128, v129
	v_pk_mul_f32 v[118:119], v[118:119], v[146:147] op_sel_hi:[1,0]
	v_cvt_pk_bf16_f32 v124, v124, v125
	v_cvt_pk_bf16_f32 v125, v150, v151
	global_store_dwordx4 v[148:149], v[122:125], off sc1
	v_pk_mul_f32 v[120:121], v[120:121], v[146:147] op_sel_hi:[1,0]
	s_andn2_b64 vcc, exec, s[4:5]
	v_pk_mul_f32 v[122:123], v[112:113], v[146:147] op_sel_hi:[1,0]
	v_pk_mul_f32 v[112:113], v[110:111], v[146:147] op_sel_hi:[1,0]
	v_cvt_pk_bf16_f32 v110, v118, v119
	v_cvt_pk_bf16_f32 v111, v120, v121
	s_mov_b64 s[4:5], -1
	v_cvt_pk_bf16_f32 v112, v112, v113
	v_cvt_pk_bf16_f32 v113, v122, v123
	ds_read_b32 v118, v152 offset:64
	global_store_dwordx4 v[148:149], v[110:113], off offset:256 sc1
	v_readlane_b32 s56, v254, 47
	s_mov_b64 s[54:55], 0x2000
	v_add_u32_e32 v110, 16, v147
	v_mad_i64_i32 v[110:111], s[26:27], v110, s96, v[140:141]
	s_waitcnt lgkmcnt(0)
	v_pk_mul_f32 v[112:113], v[116:117], v[118:119] op_sel_hi:[1,0]
	v_pk_mul_f32 v[114:115], v[114:115], v[118:119] op_sel_hi:[1,0]
	v_pk_mul_f32 v[116:117], v[108:109], v[118:119] op_sel_hi:[1,0]
	v_pk_mul_f32 v[108:109], v[106:107], v[118:119] op_sel_hi:[1,0]
	v_cvt_pk_bf16_f32 v106, v114, v115
	v_cvt_pk_bf16_f32 v107, v112, v113
	v_pk_mul_f32 v[102:103], v[102:103], v[118:119] op_sel_hi:[1,0]
	v_cvt_pk_bf16_f32 v108, v108, v109
	v_cvt_pk_bf16_f32 v109, v116, v117
	global_store_dwordx4 v[110:111], v[106:109], off sc1
	v_pk_mul_f32 v[104:105], v[104:105], v[118:119] op_sel_hi:[1,0]
	s_nop 0
	v_pk_mul_f32 v[106:107], v[96:97], v[118:119] op_sel_hi:[1,0]
	v_pk_mul_f32 v[96:97], v[94:95], v[118:119] op_sel_hi:[1,0]
	v_cvt_pk_bf16_f32 v94, v102, v103
	v_cvt_pk_bf16_f32 v95, v104, v105
	s_nop 0
	v_cvt_pk_bf16_f32 v96, v96, v97
	v_cvt_pk_bf16_f32 v97, v106, v107
	ds_read_b32 v102, v152 offset:128
	global_store_dwordx4 v[110:111], v[94:97], off offset:256 sc1
	s_waitcnt lgkmcnt(0)
	v_pk_mul_f32 v[98:99], v[98:99], v[102:103] op_sel_hi:[1,0]
	v_add_u32_e32 v94, 32, v147
	v_mad_i64_i32 v[94:95], s[26:27], v94, s96, v[140:141]
	v_pk_mul_f32 v[96:97], v[100:101], v[102:103] op_sel_hi:[1,0]
	v_pk_mul_f32 v[100:101], v[92:93], v[102:103] op_sel_hi:[1,0]
	v_pk_mul_f32 v[92:93], v[90:91], v[102:103] op_sel_hi:[1,0]
	v_cvt_pk_bf16_f32 v90, v98, v99
	v_cvt_pk_bf16_f32 v91, v96, v97
	v_pk_mul_f32 v[86:87], v[86:87], v[102:103] op_sel_hi:[1,0]
	v_cvt_pk_bf16_f32 v92, v92, v93
	v_cvt_pk_bf16_f32 v93, v100, v101
	global_store_dwordx4 v[94:95], v[90:93], off sc1
	v_pk_mul_f32 v[88:89], v[88:89], v[102:103] op_sel_hi:[1,0]
	s_nop 0
	v_pk_mul_f32 v[90:91], v[80:81], v[102:103] op_sel_hi:[1,0]
	v_pk_mul_f32 v[80:81], v[78:79], v[102:103] op_sel_hi:[1,0]
	v_cvt_pk_bf16_f32 v78, v86, v87
	v_cvt_pk_bf16_f32 v79, v88, v89
	s_nop 0
	v_cvt_pk_bf16_f32 v80, v80, v81
	v_cvt_pk_bf16_f32 v81, v90, v91
	ds_read_b32 v86, v152 offset:192
	global_store_dwordx4 v[94:95], v[78:81], off offset:256 sc1
	s_waitcnt lgkmcnt(0)
	v_pk_mul_f32 v[82:83], v[82:83], v[86:87] op_sel_hi:[1,0]
	v_add_u32_e32 v78, 48, v147
	v_mad_i64_i32 v[78:79], s[26:27], v78, s96, v[140:141]
	v_pk_mul_f32 v[80:81], v[84:85], v[86:87] op_sel_hi:[1,0]
	v_pk_mul_f32 v[84:85], v[76:77], v[86:87] op_sel_hi:[1,0]
	v_pk_mul_f32 v[76:77], v[74:75], v[86:87] op_sel_hi:[1,0]
	v_cvt_pk_bf16_f32 v74, v82, v83
	v_cvt_pk_bf16_f32 v75, v80, v81
	v_pk_mul_f32 v[70:71], v[70:71], v[86:87] op_sel_hi:[1,0]
	v_cvt_pk_bf16_f32 v76, v76, v77
	v_cvt_pk_bf16_f32 v77, v84, v85
	global_store_dwordx4 v[78:79], v[74:77], off sc1
	v_pk_mul_f32 v[72:73], v[72:73], v[86:87] op_sel_hi:[1,0]
	s_nop 0
	v_pk_mul_f32 v[74:75], v[68:69], v[86:87] op_sel_hi:[1,0]
	v_pk_mul_f32 v[68:69], v[66:67], v[86:87] op_sel_hi:[1,0]
	v_cvt_pk_bf16_f32 v66, v70, v71
	v_cvt_pk_bf16_f32 v67, v72, v73
	s_nop 0
	v_cvt_pk_bf16_f32 v68, v68, v69
	v_cvt_pk_bf16_f32 v69, v74, v75
	ds_read_b32 v70, v152 offset:512
	global_store_dwordx4 v[78:79], v[66:69], off offset:256 sc1
	s_waitcnt lgkmcnt(0)
	v_pk_mul_f32 v[64:65], v[64:65], v[70:71] op_sel_hi:[1,0]
	v_add_u32_e32 v66, 0x80, v147
	v_mad_i64_i32 v[66:67], s[26:27], v66, s96, v[140:141]
	v_pk_mul_f32 v[62:63], v[62:63], v[70:71] op_sel_hi:[1,0]
	v_pk_mul_f32 v[68:69], v[60:61], v[70:71] op_sel_hi:[1,0]
	v_pk_mul_f32 v[60:61], v[58:59], v[70:71] op_sel_hi:[1,0]
	v_cvt_pk_bf16_f32 v58, v62, v63
	v_cvt_pk_bf16_f32 v59, v64, v65
	v_pk_mul_f32 v[54:55], v[54:55], v[70:71] op_sel_hi:[1,0]
	v_cvt_pk_bf16_f32 v60, v60, v61
	v_cvt_pk_bf16_f32 v61, v68, v69
	global_store_dwordx4 v[66:67], v[58:61], off sc1
	v_pk_mul_f32 v[56:57], v[56:57], v[70:71] op_sel_hi:[1,0]
	s_nop 0
	v_pk_mul_f32 v[58:59], v[48:49], v[70:71] op_sel_hi:[1,0]
	v_pk_mul_f32 v[48:49], v[46:47], v[70:71] op_sel_hi:[1,0]
	v_cvt_pk_bf16_f32 v46, v54, v55
	v_cvt_pk_bf16_f32 v47, v56, v57
	s_nop 0
	v_cvt_pk_bf16_f32 v48, v48, v49
	v_cvt_pk_bf16_f32 v49, v58, v59
	ds_read_b32 v54, v152 offset:576
	global_store_dwordx4 v[66:67], v[46:49], off offset:256 sc1
	s_waitcnt lgkmcnt(0)
	v_pk_mul_f32 v[50:51], v[50:51], v[54:55] op_sel_hi:[1,0]
	v_add_u32_e32 v46, 0x90, v147
	v_mad_i64_i32 v[46:47], s[26:27], v46, s96, v[140:141]
	v_pk_mul_f32 v[48:49], v[52:53], v[54:55] op_sel_hi:[1,0]
	v_pk_mul_f32 v[52:53], v[44:45], v[54:55] op_sel_hi:[1,0]
	v_pk_mul_f32 v[44:45], v[42:43], v[54:55] op_sel_hi:[1,0]
	v_cvt_pk_bf16_f32 v42, v50, v51
	v_cvt_pk_bf16_f32 v43, v48, v49
	v_pk_mul_f32 v[38:39], v[38:39], v[54:55] op_sel_hi:[1,0]
	v_cvt_pk_bf16_f32 v44, v44, v45
	v_cvt_pk_bf16_f32 v45, v52, v53
	global_store_dwordx4 v[46:47], v[42:45], off sc1
	v_pk_mul_f32 v[40:41], v[40:41], v[54:55] op_sel_hi:[1,0]
	s_nop 0
	v_pk_mul_f32 v[42:43], v[32:33], v[54:55] op_sel_hi:[1,0]
	v_pk_mul_f32 v[32:33], v[30:31], v[54:55] op_sel_hi:[1,0]
	v_cvt_pk_bf16_f32 v30, v38, v39
	v_cvt_pk_bf16_f32 v31, v40, v41
	s_nop 0
	v_cvt_pk_bf16_f32 v32, v32, v33
	v_cvt_pk_bf16_f32 v33, v42, v43
	ds_read_b32 v38, v152 offset:640
	global_store_dwordx4 v[46:47], v[30:33], off offset:256 sc1
	s_waitcnt lgkmcnt(0)
	v_pk_mul_f32 v[34:35], v[34:35], v[38:39] op_sel_hi:[1,0]
	v_add_u32_e32 v30, 0xa0, v147
	v_mad_i64_i32 v[30:31], s[26:27], v30, s96, v[140:141]
	v_pk_mul_f32 v[32:33], v[36:37], v[38:39] op_sel_hi:[1,0]
	v_pk_mul_f32 v[36:37], v[28:29], v[38:39] op_sel_hi:[1,0]
	v_pk_mul_f32 v[28:29], v[26:27], v[38:39] op_sel_hi:[1,0]
	v_cvt_pk_bf16_f32 v26, v34, v35
	v_cvt_pk_bf16_f32 v27, v32, v33
	v_pk_mul_f32 v[22:23], v[22:23], v[38:39] op_sel_hi:[1,0]
	v_cvt_pk_bf16_f32 v28, v28, v29
	v_cvt_pk_bf16_f32 v29, v36, v37
	global_store_dwordx4 v[30:31], v[26:29], off sc1
	v_pk_mul_f32 v[24:25], v[24:25], v[38:39] op_sel_hi:[1,0]
	s_nop 0
	v_pk_mul_f32 v[26:27], v[16:17], v[38:39] op_sel_hi:[1,0]
	v_pk_mul_f32 v[16:17], v[14:15], v[38:39] op_sel_hi:[1,0]
	v_cvt_pk_bf16_f32 v14, v22, v23
	v_cvt_pk_bf16_f32 v15, v24, v25
	s_nop 0
	v_cvt_pk_bf16_f32 v16, v16, v17
	v_cvt_pk_bf16_f32 v17, v26, v27
	ds_read_b32 v22, v152 offset:704
	global_store_dwordx4 v[30:31], v[14:17], off offset:256 sc1
	s_waitcnt lgkmcnt(0)
	v_pk_mul_f32 v[18:19], v[18:19], v[22:23] op_sel_hi:[1,0]
	v_add_u32_e32 v14, 0xb0, v147
	v_mad_i64_i32 v[14:15], s[26:27], v14, s96, v[140:141]
	v_pk_mul_f32 v[16:17], v[20:21], v[22:23] op_sel_hi:[1,0]
	v_pk_mul_f32 v[20:21], v[12:13], v[22:23] op_sel_hi:[1,0]
	v_pk_mul_f32 v[12:13], v[10:11], v[22:23] op_sel_hi:[1,0]
	v_cvt_pk_bf16_f32 v10, v18, v19
	v_cvt_pk_bf16_f32 v11, v16, v17
	v_pk_mul_f32 v[8:9], v[8:9], v[22:23] op_sel_hi:[1,0]
	v_cvt_pk_bf16_f32 v12, v12, v13
	v_cvt_pk_bf16_f32 v13, v20, v21
	global_store_dwordx4 v[14:15], v[10:13], off sc1
	v_pk_mul_f32 v[6:7], v[6:7], v[22:23] op_sel_hi:[1,0]
	s_nop 0
	v_pk_mul_f32 v[10:11], v[4:5], v[22:23] op_sel_hi:[1,0]
	v_pk_mul_f32 v[4:5], v[2:3], v[22:23] op_sel_hi:[1,0]
	v_cvt_pk_bf16_f32 v2, v6, v7
	v_cvt_pk_bf16_f32 v3, v8, v9
	s_nop 0
	v_cvt_pk_bf16_f32 v4, v4, v5
	v_cvt_pk_bf16_f32 v5, v10, v11
	global_store_dwordx4 v[14:15], v[2:5], off offset:256 sc1
	s_cbranch_vccnz .LBB0_439
	s_andn2_b64 vcc, exec, s[12:13]
	s_cbranch_vccnz .LBB0_438
	s_barrier
	s_branch .LBB0_438
